# attention exp/PV block: first V fragment reads issued ahead of the wait for the early K-fragment reads (counted lgkmcnt)
# baseline (speedup 1.0000x reference)
.Lattn_855i:
	v_lshl_add_u32 v205, s62, 13, v202
	ds_read_b64_tr_b16 v[156:157], v205 offset:36864
	ds_read_b64_tr_b16 v[158:159], v205 offset:37376
	ds_read_b64_tr_b16 v[164:165], v205 offset:40960
	ds_read_b64_tr_b16 v[166:167], v205 offset:41472
	s_waitcnt lgkmcnt(4)
	v_exp_f32_e32 v48, v48
	v_exp_f32_e32 v49, v49
	v_exp_f32_e32 v50, v50
	v_exp_f32_e32 v51, v51
	v_mfma_f32_32x32x16_bf16 v[96:111], v[206:209], v[128:131], v[80:95]
	ds_read_b128 v[206:209], v253 offset:8704
	v_exp_f32_e32 v52, v52
	v_exp_f32_e32 v53, v53
	v_exp_f32_e32 v54, v54
	v_exp_f32_e32 v55, v55
	v_mfma_f32_32x32x16_bf16 v[112:127], v[210:213], v[128:131], v[80:95]
	ds_read_b128 v[210:213], v253 offset:10240
	v_cvt_pk_bf16_f32 v152, v48, v49
	v_add_f32_e32 v230, v230, v48
	v_add_f32_e32 v252, v252, v49
	v_cvt_pk_bf16_f32 v153, v50, v51
	v_mfma_f32_32x32x16_bf16 v[96:111], v[214:217], v[132:135], v[96:111]
	ds_read_b128 v[214:217], v253 offset:10752
	v_add_f32_e32 v230, v230, v50
	v_add_f32_e32 v252, v252, v51
	v_cvt_pk_bf16_f32 v154, v52, v53
	v_add_f32_e32 v230, v230, v52
	v_mfma_f32_32x32x16_bf16 v[112:127], v[218:221], v[132:135], v[112:127]
	v_add_f32_e32 v252, v252, v53
	v_cvt_pk_bf16_f32 v155, v54, v55
	v_add_f32_e32 v230, v230, v54
	v_add_f32_e32 v252, v252, v55
	v_mfma_f32_32x32x16_bf16 v[96:111], v[222:225], v[136:139], v[96:111]
	v_exp_f32_e32 v56, v56
	v_exp_f32_e32 v57, v57
	v_exp_f32_e32 v58, v58
	v_exp_f32_e32 v59, v59
	s_waitcnt lgkmcnt(5)
	v_mfma_f32_32x32x16_bf16 v[0:15], v[152:155], v[156:159], v[0:15]
	ds_read_b64_tr_b16 v[218:219], v205 offset:37888
	ds_read_b64_tr_b16 v[220:221], v205 offset:38400
	ds_read_b64_tr_b16 v[222:223], v205 offset:41984
	ds_read_b64_tr_b16 v[224:225], v205 offset:42496
	v_exp_f32_e32 v60, v60
	v_exp_f32_e32 v61, v61
	v_exp_f32_e32 v62, v62
	v_exp_f32_e32 v63, v63
	s_waitcnt lgkmcnt(7)
	v_mfma_f32_32x32x16_bf16 v[16:31], v[152:155], v[164:167], v[16:31]
	v_cvt_pk_bf16_f32 v160, v56, v57
	v_add_f32_e32 v230, v230, v56
	v_add_f32_e32 v252, v252, v57
	v_cvt_pk_bf16_f32 v161, v58, v59
	v_mfma_f32_32x32x16_bf16 v[112:127], v[226:229], v[136:139], v[112:127]
	ds_read_b64_tr_b16 v[156:157], v205 offset:38912
	ds_read_b64_tr_b16 v[158:159], v205 offset:39424
	ds_read_b64_tr_b16 v[164:165], v205 offset:43008
	ds_read_b64_tr_b16 v[166:167], v205 offset:43520
	v_add_f32_e32 v230, v230, v58
	v_add_f32_e32 v252, v252, v59
	v_cvt_pk_bf16_f32 v162, v60, v61
	v_add_f32_e32 v230, v230, v60
	v_mfma_f32_32x32x16_bf16 v[96:111], v[236:239], v[140:143], v[96:111]
	v_add_f32_e32 v252, v252, v61
	v_cvt_pk_bf16_f32 v163, v62, v63
	v_add_f32_e32 v230, v230, v62
	v_add_f32_e32 v252, v252, v63
	v_mfma_f32_32x32x16_bf16 v[112:127], v[240:243], v[140:143], v[112:127]
	v_exp_f32_e32 v64, v64
	v_exp_f32_e32 v65, v65
	v_exp_f32_e32 v66, v66
	v_exp_f32_e32 v67, v67
	s_waitcnt lgkmcnt(6)
	v_mfma_f32_32x32x16_bf16 v[0:15], v[160:163], v[218:221], v[0:15]
	v_exp_f32_e32 v68, v68
	v_exp_f32_e32 v69, v69
	v_exp_f32_e32 v70, v70
	v_exp_f32_e32 v71, v71
	s_waitcnt lgkmcnt(4)
	v_mfma_f32_32x32x16_bf16 v[16:31], v[160:163], v[222:225], v[16:31]
	v_cvt_pk_bf16_f32 v152, v64, v65
	v_add_f32_e32 v230, v230, v64
	v_add_f32_e32 v252, v252, v65
	v_cvt_pk_bf16_f32 v153, v66, v67
	v_mfma_f32_32x32x16_bf16 v[96:111], v[248:251], v[144:147], v[96:111]
	ds_read_b64_tr_b16 v[218:219], v205 offset:39936
	ds_read_b64_tr_b16 v[220:221], v205 offset:40448
	ds_read_b64_tr_b16 v[222:223], v205 offset:44032
	ds_read_b64_tr_b16 v[224:225], v205 offset:44544
	v_add_f32_e32 v230, v230, v66
	v_add_f32_e32 v252, v252, v67
	v_cvt_pk_bf16_f32 v154, v68, v69
	v_add_f32_e32 v230, v230, v68
	v_mfma_f32_32x32x16_bf16 v[112:127], v[206:209], v[144:147], v[112:127]
	v_add_f32_e32 v252, v252, v69
	v_cvt_pk_bf16_f32 v155, v70, v71
	v_add_f32_e32 v230, v230, v70
	v_add_f32_e32 v252, v252, v71
	s_waitcnt lgkmcnt(6)
	v_mfma_f32_32x32x16_bf16 v[0:15], v[152:155], v[156:159], v[0:15]
	v_exp_f32_e32 v72, v72
	v_exp_f32_e32 v73, v73
	v_exp_f32_e32 v74, v74
	v_exp_f32_e32 v75, v75
	s_waitcnt lgkmcnt(4)
	v_mfma_f32_32x32x16_bf16 v[16:31], v[152:155], v[164:167], v[16:31]
	v_exp_f32_e32 v76, v76
	v_exp_f32_e32 v77, v77
	v_exp_f32_e32 v78, v78
	v_exp_f32_e32 v79, v79
	v_mfma_f32_32x32x16_bf16 v[96:111], v[210:213], v[148:151], v[96:111]
	v_cvt_pk_bf16_f32 v160, v72, v73
	v_add_f32_e32 v230, v230, v72
	v_add_f32_e32 v252, v252, v73
	v_cvt_pk_bf16_f32 v161, v74, v75
	v_mfma_f32_32x32x16_bf16 v[112:127], v[214:217], v[148:151], v[112:127]
	v_add_f32_e32 v230, v230, v74
	v_add_f32_e32 v252, v252, v75
	v_cvt_pk_bf16_f32 v162, v76, v77
	v_add_f32_e32 v230, v230, v76
	v_add_f32_e32 v252, v252, v77
	v_cvt_pk_bf16_f32 v163, v78, v79
	v_add_f32_e32 v230, v230, v78
	v_add_f32_e32 v252, v252, v79
	s_waitcnt lgkmcnt(2)
	v_mfma_f32_32x32x16_bf16 v[0:15], v[160:163], v[218:221], v[0:15]
	s_waitcnt lgkmcnt(0)
	v_mfma_f32_32x32x16_bf16 v[16:31], v[160:163], v[222:225], v[16:31]
	s_branch .Lattn_855_end
.Lattn_869i:
	v_lshl_add_u32 v205, s19, 13, v202
	ds_read_b64_tr_b16 v[156:157], v205 offset:36864
	ds_read_b64_tr_b16 v[158:159], v205 offset:37376
	ds_read_b64_tr_b16 v[164:165], v205 offset:40960
	ds_read_b64_tr_b16 v[166:167], v205 offset:41472
	s_waitcnt lgkmcnt(4)
	v_exp_f32_e32 v96, v96
	v_exp_f32_e32 v97, v97
	v_exp_f32_e32 v98, v98
	v_exp_f32_e32 v99, v99
	v_mfma_f32_32x32x16_bf16 v[48:63], v[206:209], v[128:131], v[80:95]
	ds_read_b128 v[206:209], v253 offset:8704
	v_exp_f32_e32 v100, v100
	v_exp_f32_e32 v101, v101
	v_exp_f32_e32 v102, v102
	v_exp_f32_e32 v103, v103
	v_mfma_f32_32x32x16_bf16 v[64:79], v[210:213], v[128:131], v[80:95]
	ds_read_b128 v[210:213], v253 offset:10240
	v_cvt_pk_bf16_f32 v152, v96, v97
	v_add_f32_e32 v230, v230, v96
	v_add_f32_e32 v252, v252, v97
	v_cvt_pk_bf16_f32 v153, v98, v99
	v_mfma_f32_32x32x16_bf16 v[48:63], v[214:217], v[132:135], v[48:63]
	ds_read_b128 v[214:217], v253 offset:10752
	v_add_f32_e32 v230, v230, v98
	v_add_f32_e32 v252, v252, v99
	v_cvt_pk_bf16_f32 v154, v100, v101
	v_add_f32_e32 v230, v230, v100
	v_mfma_f32_32x32x16_bf16 v[64:79], v[218:221], v[132:135], v[64:79]
	v_add_f32_e32 v252, v252, v101
	v_cvt_pk_bf16_f32 v155, v102, v103
	v_add_f32_e32 v230, v230, v102
	v_add_f32_e32 v252, v252, v103
	v_mfma_f32_32x32x16_bf16 v[48:63], v[222:225], v[136:139], v[48:63]
	v_exp_f32_e32 v104, v104
	v_exp_f32_e32 v105, v105
	v_exp_f32_e32 v106, v106
	v_exp_f32_e32 v107, v107
	s_waitcnt lgkmcnt(5)
	v_mfma_f32_32x32x16_bf16 v[0:15], v[152:155], v[156:159], v[0:15]
	ds_read_b64_tr_b16 v[218:219], v205 offset:37888
	ds_read_b64_tr_b16 v[220:221], v205 offset:38400
	ds_read_b64_tr_b16 v[222:223], v205 offset:41984
	ds_read_b64_tr_b16 v[224:225], v205 offset:42496
	v_exp_f32_e32 v108, v108
	v_exp_f32_e32 v109, v109
	v_exp_f32_e32 v110, v110
	v_exp_f32_e32 v111, v111
	s_waitcnt lgkmcnt(7)
	v_mfma_f32_32x32x16_bf16 v[16:31], v[152:155], v[164:167], v[16:31]
	v_cvt_pk_bf16_f32 v160, v104, v105
	v_add_f32_e32 v230, v230, v104
	v_add_f32_e32 v252, v252, v105
	v_cvt_pk_bf16_f32 v161, v106, v107
	v_mfma_f32_32x32x16_bf16 v[64:79], v[226:229], v[136:139], v[64:79]
	ds_read_b64_tr_b16 v[156:157], v205 offset:38912
	ds_read_b64_tr_b16 v[158:159], v205 offset:39424
	ds_read_b64_tr_b16 v[164:165], v205 offset:43008
	ds_read_b64_tr_b16 v[166:167], v205 offset:43520
	v_add_f32_e32 v230, v230, v106
	v_add_f32_e32 v252, v252, v107
	v_cvt_pk_bf16_f32 v162, v108, v109
	v_add_f32_e32 v230, v230, v108
	v_mfma_f32_32x32x16_bf16 v[48:63], v[236:239], v[140:143], v[48:63]
	v_add_f32_e32 v252, v252, v109
	v_cvt_pk_bf16_f32 v163, v110, v111
	v_add_f32_e32 v230, v230, v110
	v_add_f32_e32 v252, v252, v111
	v_mfma_f32_32x32x16_bf16 v[64:79], v[240:243], v[140:143], v[64:79]
	v_exp_f32_e32 v112, v112
	v_exp_f32_e32 v113, v113
	v_exp_f32_e32 v114, v114
	v_exp_f32_e32 v115, v115
	s_waitcnt lgkmcnt(6)
	v_mfma_f32_32x32x16_bf16 v[0:15], v[160:163], v[218:221], v[0:15]
	v_exp_f32_e32 v116, v116
	v_exp_f32_e32 v117, v117
	v_exp_f32_e32 v118, v118
	v_exp_f32_e32 v119, v119
	s_waitcnt lgkmcnt(4)
	v_mfma_f32_32x32x16_bf16 v[16:31], v[160:163], v[222:225], v[16:31]
	v_cvt_pk_bf16_f32 v152, v112, v113
	v_add_f32_e32 v230, v230, v112
	v_add_f32_e32 v252, v252, v113
	v_cvt_pk_bf16_f32 v153, v114, v115
	v_mfma_f32_32x32x16_bf16 v[48:63], v[248:251], v[144:147], v[48:63]
	ds_read_b64_tr_b16 v[218:219], v205 offset:39936
	ds_read_b64_tr_b16 v[220:221], v205 offset:40448
	ds_read_b64_tr_b16 v[222:223], v205 offset:44032
	ds_read_b64_tr_b16 v[224:225], v205 offset:44544
	v_add_f32_e32 v230, v230, v114
	v_add_f32_e32 v252, v252, v115
	v_cvt_pk_bf16_f32 v154, v116, v117
	v_add_f32_e32 v230, v230, v116
	v_mfma_f32_32x32x16_bf16 v[64:79], v[206:209], v[144:147], v[64:79]
	v_add_f32_e32 v252, v252, v117
	v_cvt_pk_bf16_f32 v155, v118, v119
	v_add_f32_e32 v230, v230, v118
	v_add_f32_e32 v252, v252, v119
	s_waitcnt lgkmcnt(6)
	v_mfma_f32_32x32x16_bf16 v[0:15], v[152:155], v[156:159], v[0:15]
	v_exp_f32_e32 v120, v120
	v_exp_f32_e32 v121, v121
	v_exp_f32_e32 v122, v122
	v_exp_f32_e32 v123, v123
	s_waitcnt lgkmcnt(4)
	v_mfma_f32_32x32x16_bf16 v[16:31], v[152:155], v[164:167], v[16:31]
	v_exp_f32_e32 v124, v124
	v_exp_f32_e32 v125, v125
	v_exp_f32_e32 v126, v126
	v_exp_f32_e32 v127, v127
	v_mfma_f32_32x32x16_bf16 v[48:63], v[210:213], v[148:151], v[48:63]
	v_cvt_pk_bf16_f32 v160, v120, v121
	v_add_f32_e32 v230, v230, v120
	v_add_f32_e32 v252, v252, v121
	v_cvt_pk_bf16_f32 v161, v122, v123
	v_mfma_f32_32x32x16_bf16 v[64:79], v[214:217], v[148:151], v[64:79]
	v_add_f32_e32 v230, v230, v122
	v_add_f32_e32 v252, v252, v123
	v_cvt_pk_bf16_f32 v162, v124, v125
	v_add_f32_e32 v230, v230, v124
	v_add_f32_e32 v252, v252, v125
	v_cvt_pk_bf16_f32 v163, v126, v127
	v_add_f32_e32 v230, v230, v126
	v_add_f32_e32 v252, v252, v127
	s_waitcnt lgkmcnt(2)
	v_mfma_f32_32x32x16_bf16 v[0:15], v[160:163], v[218:221], v[0:15]
	s_waitcnt lgkmcnt(0)
	v_mfma_f32_32x32x16_bf16 v[16:31], v[160:163], v[222:225], v[16:31]
	s_branch .LBB0_870
